# attention queue order: each XCD finishes one (batch,kv-head) group before the next (smaller L2 working set); same units, same math
# baseline (speedup 1.0000x reference)
.LBB0_462:
	s_and_b64 vcc, exec, s[4:5]
	s_cbranch_vccz .LBB0_438
	s_lshr_b32 s4, s12, 3
	s_and_b32 s5, s4, 31
	s_lshr_b32 s4, s4, 5
	s_mul_i32 s4, s4, s36
	v_mov_b32_e32 v195, v194
	s_add_i32 s4, s4, s80
	s_lshl_b32 s6, s12, 4
	s_and_b32 s24, s4, 1
	v_lshlrev_b32_e32 v0, 7, v195
	s_lshl_b32 s5, s5, 7
	s_and_b32 s6, s6, 0x70
	v_and_b32_e32 v0, 0x180, v0
	s_sub_i32 s76, s6, s5
	v_lshl_or_b32 v0, s24, 9, v0
	s_add_i32 s45, s76, 0xf80
	v_lshl_add_u64 v[6:7], v[154:155], 0, v[0:1]
	v_bfe_u32 v0, v195, 2, 3
	s_ashr_i32 s16, s4, 1
	v_ashrrev_i32_e32 v4, 5, v195
	v_or_b32_e32 v172, s45, v0
	s_ashr_i32 s17, s16, 31
	v_lshlrev_b32_e32 v2, 3, v4
	v_or_b32_e32 v174, 8, v172
	s_lshl_b64 s[6:7], s[16:17], 12
	v_ashrrev_i32_e32 v3, 31, v2
	v_ashrrev_i32_e32 v173, 31, v172
	v_ashrrev_i32_e32 v175, 31, v174
	v_lshl_add_u64 v[6:7], v[2:3], 1, v[6:7]
	v_lshl_add_u64 v[170:171], s[6:7], 0, v[172:173]
	v_lshl_add_u64 v[168:169], s[6:7], 0, v[174:175]
	v_mad_u64_u32 v[8:9], s[8:9], v170, s61, v[6:7]
	v_mad_u64_u32 v[6:7], s[6:7], v168, s61, v[6:7]
	v_mad_i32_i24 v9, v171, s61, v9
	v_mad_i32_i24 v7, v169, s61, v7
	global_load_dwordx4 v[82:85], v[8:9], off
	global_load_dwordx4 v[86:89], v[8:9], off offset:32
	global_load_dwordx4 v[90:93], v[8:9], off offset:64
	global_load_dwordx4 v[94:97], v[8:9], off offset:96
	global_load_dwordx4 v[98:101], v[6:7], off
	global_load_dwordx4 v[102:105], v[6:7], off offset:32
	global_load_dwordx4 v[106:109], v[6:7], off offset:64
	global_load_dwordx4 v[110:113], v[6:7], off offset:96
	s_ashr_i32 s5, s4, 31
	s_lshl_b64 s[4:5], s[4:5], 15
	s_add_i32 s8, s76, 0xf70
	s_cmp_gt_i32 s45, 15
	s_cselect_b64 s[6:7], -1, 0
	s_lshr_b32 s10, s8, 9
	s_cmp_lt_i32 s45, 16
	s_cbranch_scc1 .LBB0_477
	v_and_b32_e32 v5, 31, v195
	v_lshl_add_u64 v[6:7], v[156:157], 0, s[4:5]
	v_lshlrev_b32_e32 v0, 7, v5
	v_lshl_add_u64 v[6:7], v[6:7], 0, v[0:1]
	v_lshlrev_b64 v[2:3], 1, v[2:3]
	v_lshl_add_u64 v[148:149], v[6:7], 0, v[2:3]
	global_load_dwordx4 v[114:117], v[148:149], off offset:96
	global_load_dwordx4 v[118:121], v[148:149], off offset:64
	global_load_dwordx4 v[122:125], v[148:149], off offset:32
	global_load_dwordx4 v[126:129], v[148:149], off
	v_lshl_add_u64 v[6:7], v[158:159], 0, s[4:5]
	v_lshl_add_u64 v[2:3], v[6:7], 0, v[2:3]
	v_lshlrev_b32_e32 v0, 5, v5
	v_mov_b32_e32 v14, v1
	v_mov_b32_e32 v15, v1
	v_lshl_add_u64 v[150:151], v[2:3], 0, v[0:1]
	v_lshlrev_b32_e32 v152, 6, v4
	v_mov_b32_e32 v0, v1
	v_mov_b32_e32 v2, v1
	v_mov_b32_e32 v3, v1
	v_mov_b32_e32 v4, v1
	v_mov_b32_e32 v5, v1
	v_mov_b32_e32 v6, v1
	v_mov_b32_e32 v7, v1
	v_mov_b32_e32 v8, v1
	v_mov_b32_e32 v9, v1
	v_mov_b32_e32 v10, v1
	v_mov_b32_e32 v11, v1
	v_mov_b32_e32 v12, v1
	v_mov_b32_e32 v13, v1
	v_mov_b64_e32 v[64:65], v[14:15]
	v_mov_b64_e32 v[80:81], v[14:15]
	v_mov_b64_e32 v[48:49], v[14:15]
	v_mov_b64_e32 v[32:33], v[14:15]
	s_mov_b32 s11, 0
	v_mov_b32_e32 v153, 0xf149f2ca
	v_mov_b32_e32 v147, 0
	s_movk_i32 s12, 0x20f
	v_mov_b32_e32 v146, 0
	v_mov_b32_e32 v173, 0xf149f2ca
	v_mov_b32_e32 v189, 0xf149f2ca
	v_mov_b64_e32 v[62:63], v[12:13]
	v_mov_b64_e32 v[60:61], v[10:11]
	v_mov_b64_e32 v[58:59], v[8:9]
	v_mov_b64_e32 v[56:57], v[6:7]
	v_mov_b64_e32 v[54:55], v[4:5]
	v_mov_b64_e32 v[52:53], v[2:3]
	v_mov_b64_e32 v[50:51], v[0:1]
	v_mov_b64_e32 v[78:79], v[12:13]
	v_mov_b64_e32 v[76:77], v[10:11]
	v_mov_b64_e32 v[74:75], v[8:9]
	v_mov_b64_e32 v[72:73], v[6:7]
	v_mov_b64_e32 v[70:71], v[4:5]
	v_mov_b64_e32 v[68:69], v[2:3]
	v_mov_b64_e32 v[66:67], v[0:1]
	v_mov_b32_e32 v175, 0xf149f2ca
	v_mov_b64_e32 v[46:47], v[12:13]
	v_mov_b64_e32 v[44:45], v[10:11]
	v_mov_b64_e32 v[42:43], v[8:9]
	v_mov_b64_e32 v[40:41], v[6:7]
	v_mov_b64_e32 v[38:39], v[4:5]
	v_mov_b64_e32 v[36:37], v[2:3]
	v_mov_b64_e32 v[34:35], v[0:1]
	v_mov_b64_e32 v[30:31], v[12:13]
	v_mov_b64_e32 v[28:29], v[10:11]
	v_mov_b64_e32 v[26:27], v[8:9]
	v_mov_b64_e32 v[24:25], v[6:7]
	v_mov_b64_e32 v[22:23], v[4:5]
	v_mov_b64_e32 v[20:21], v[2:3]
	v_mov_b64_e32 v[18:19], v[0:1]
